# grid barrier: non-leader workgroups issue the agent-scope L1 invalidate (buffer_inv sc1) when they start waiting for the XCD release instead of after observing it (its ~1.7us latency hides under the w
# speedup vs baseline: 1.0066x; 1.0066x over previous
.LBB0_37:
	s_or_b64 exec, exec, s[10:11]
	v_cvt_f32_u32_e32 v5, v3
	s_waitcnt vmcnt(0)
	v_readfirstlane_b32 s6, v4
	v_sub_u32_e32 v4, 0, v3
	v_rcp_iflag_f32_e32 v5, v5
	v_add_u32_e32 v6, s6, v2
	v_mul_f32_e32 v5, 0x4f7ffffe, v5
	v_cvt_u32_f32_e32 v5, v5
	v_mul_lo_u32 v2, v4, v5
	v_mul_hi_u32 v2, v5, v2
	v_add_u32_e32 v2, v5, v2
	v_mul_hi_u32 v2, v6, v2
	v_mul_lo_u32 v4, v2, v3
	v_sub_u32_e32 v4, v6, v4
	v_add_u32_e32 v5, 1, v2
	v_cmp_ge_u32_e32 vcc, v4, v3
	s_nop 1
	v_cndmask_b32_e32 v2, v2, v5, vcc
	v_sub_u32_e32 v5, v4, v3
	v_cndmask_b32_e32 v4, v4, v5, vcc
	v_add_u32_e32 v5, 1, v2
	v_cmp_ge_u32_e32 vcc, v4, v3
	v_add_u32_e32 v4, 1, v6
	s_nop 0
	v_cndmask_b32_e32 v2, v2, v5, vcc
	v_mul_lo_u32 v5, v3, v2
	v_add_u32_e32 v3, v5, v3
	v_cmp_ne_u32_e32 vcc, v4, v3
	s_and_saveexec_b64 s[6:7], vcc
	s_xor_b64 s[6:7], exec, s[6:7]
	s_cbranch_execz .LBB0_51
	s_waitcnt lgkmcnt(0)
	buffer_inv sc1
	v_mov_b32_e32 v1, 0x2000
	global_load_dword v1, v1, s[4:5] offset:1024 sc1
	s_add_u32 s12, s4, 0x2400
	s_addc_u32 s13, s5, 0
	s_waitcnt vmcnt(0)
	v_cmp_eq_u32_e32 vcc, v1, v2
	s_and_saveexec_b64 s[10:11], vcc
	s_cbranch_execz .LBB0_50
	s_mov_b32 s26, 1
	s_mov_b64 s[16:17], 0
	v_mov_b32_e32 v1, 0
	s_branch .LBB0_41

.LBB0_50:
	s_or_b64 exec, exec, s[10:11]
	s_waitcnt vmcnt(0)
	s_waitcnt vmcnt(0)

.LBB0_238:
	s_or_b64 exec, exec, s[8:9]
	v_cvt_f32_u32_e32 v5, v3
	s_waitcnt vmcnt(0)
	v_readfirstlane_b32 s6, v4
	v_sub_u32_e32 v4, 0, v3
	v_rcp_iflag_f32_e32 v5, v5
	v_add_u32_e32 v6, s6, v2
	v_mul_f32_e32 v5, 0x4f7ffffe, v5
	v_cvt_u32_f32_e32 v5, v5
	v_mul_lo_u32 v2, v4, v5
	v_mul_hi_u32 v2, v5, v2
	v_add_u32_e32 v2, v5, v2
	v_mul_hi_u32 v2, v6, v2
	v_mul_lo_u32 v4, v2, v3
	v_sub_u32_e32 v4, v6, v4
	v_add_u32_e32 v5, 1, v2
	v_cmp_ge_u32_e32 vcc, v4, v3
	s_nop 1
	v_cndmask_b32_e32 v2, v2, v5, vcc
	v_sub_u32_e32 v5, v4, v3
	v_cndmask_b32_e32 v4, v4, v5, vcc
	v_add_u32_e32 v5, 1, v2
	v_cmp_ge_u32_e32 vcc, v4, v3
	v_add_u32_e32 v4, 1, v6
	s_nop 0
	v_cndmask_b32_e32 v2, v2, v5, vcc
	v_mul_lo_u32 v5, v3, v2
	v_add_u32_e32 v3, v5, v3
	v_cmp_ne_u32_e32 vcc, v4, v3
	s_and_saveexec_b64 s[6:7], vcc
	s_xor_b64 s[6:7], exec, s[6:7]
	s_cbranch_execz .LBB0_252
	s_waitcnt lgkmcnt(0)
	buffer_inv sc1
	v_mov_b32_e32 v1, 0x2000
	global_load_dword v1, v1, s[4:5] offset:1024 sc1
	s_add_u32 s10, s4, 0x2400
	s_addc_u32 s11, s5, 0
	s_waitcnt vmcnt(0)
	v_cmp_eq_u32_e32 vcc, v1, v2
	s_and_saveexec_b64 s[8:9], vcc
	s_cbranch_execz .LBB0_251
	s_mov_b32 s24, 1
	s_mov_b64 s[12:13], 0
	v_mov_b32_e32 v1, 0
	s_branch .LBB0_242

.LBB0_251:
	s_or_b64 exec, exec, s[8:9]
	s_waitcnt vmcnt(0)
	s_waitcnt vmcnt(0)

.LBB0_576:
	s_or_b64 exec, exec, s[8:9]
	v_cvt_f32_u32_e32 v4, v2
	s_waitcnt vmcnt(0)
	v_readfirstlane_b32 s5, v3
	v_sub_u32_e32 v3, 0, v2
	v_rcp_iflag_f32_e32 v4, v4
	v_add_u32_e32 v5, s5, v1
	v_mul_f32_e32 v4, 0x4f7ffffe, v4
	v_cvt_u32_f32_e32 v4, v4
	v_mul_lo_u32 v1, v3, v4
	v_mul_hi_u32 v1, v4, v1
	v_add_u32_e32 v1, v4, v1
	v_mul_hi_u32 v1, v5, v1
	v_mul_lo_u32 v3, v1, v2
	v_sub_u32_e32 v3, v5, v3
	v_add_u32_e32 v4, 1, v1
	v_cmp_ge_u32_e32 vcc, v3, v2
	s_nop 1
	v_cndmask_b32_e32 v1, v1, v4, vcc
	v_sub_u32_e32 v4, v3, v2
	v_cndmask_b32_e32 v3, v3, v4, vcc
	v_add_u32_e32 v4, 1, v1
	v_cmp_ge_u32_e32 vcc, v3, v2
	v_add_u32_e32 v3, 1, v5
	s_nop 0
	v_cndmask_b32_e32 v1, v1, v4, vcc
	v_mul_lo_u32 v4, v2, v1
	v_add_u32_e32 v2, v4, v2
	v_cmp_ne_u32_e32 vcc, v3, v2
	s_and_saveexec_b64 s[8:9], vcc
	s_xor_b64 s[8:9], exec, s[8:9]
	s_cbranch_execz .LBB0_590
	v_readlane_b32 s10, v253, 20
	v_readlane_b32 s11, v253, 21
	s_waitcnt lgkmcnt(0)
	buffer_inv sc1
	s_nop 3
	global_load_dword v0, v33, s[10:11] sc1
	s_waitcnt vmcnt(0)
	v_cmp_eq_u32_e32 vcc, v0, v1
	s_and_saveexec_b64 s[10:11], vcc
	s_cbranch_execz .LBB0_589
	s_mov_b32 s5, 1
	s_mov_b64 s[12:13], 0
	s_branch .LBB0_580
